# NSA selected loop: skip a row tile's QK/softmax/PV when none of its 16 q-rows selects the key tile (contribution exactly zero)
# speedup vs baseline: 1.0063x; 1.0063x over previous
.LBB0_868:
	s_and_b32 s44, s2, 1
	s_xor_b32 s49, s44, 1
	s_mulk_i32 s49, 0x2400
	s_mulk_i32 s44, 0x2400
	v_add_u32_e32 v80, s44, v129
	v_add_u32_e32 v113, s49, v127
	v_add_u32_e32 v76, s44, v167
	ds_read_b128 v[202:205], v80 offset:4608
	ds_read_b128 v[206:209], v80 offset:4672
	ds_read_b128 v[210:213], v80 offset:6912
	ds_read_b128 v[218:221], v80 offset:6976
	v_lshrrev_b64 v[246:247], s2, v[72:73]
	v_lshrrev_b64 v[244:245], s2, v[74:75]
	v_add_u32_e32 v80, s49, v129
	v_and_b32_e32 v243, 1, v246
	v_and_b32_e32 v245, 1, v244
	v_cmp_ne_u32_e32 vcc, 0, v243
	s_cmp_lg_u64 vcc, 0
	s_cselect_b32 s48, 1, 0
	v_cmp_ne_u32_e32 vcc, 0, v245
	s_cmp_lg_u64 vcc, 0
	s_cselect_b32 s49, 2, 0
	s_or_b32 s48, s48, s49
	s_cmp_eq_u32 s48, 3
	s_cbranch_scc0 .Lsel5_disp
	v_not_b32_e32 v246, v246
	v_bfe_i32 v246, v246, 0, 1
	v_not_b32_e32 v247, v244
	v_bfe_i32 v247, v247, 0, 1
	v_and_b32_e32 v238, 0xf149f2ca, v246
	v_and_b32_e32 v242, 0xf149f2ca, v247
	v_and_b32_e32 v239, 0xf149f2ca, v246
	v_and_b32_e32 v243, 0xf149f2ca, v247
	v_and_b32_e32 v240, 0xf149f2ca, v246
	v_and_b32_e32 v244, 0xf149f2ca, v247
	v_and_b32_e32 v241, 0xf149f2ca, v246
	v_and_b32_e32 v245, 0xf149f2ca, v247
	s_waitcnt lgkmcnt(5)
	v_mfma_f32_16x16x32_bf16 v[64:67], v[186:189], v[0:3], v[238:241]
	v_mfma_f32_16x16x32_bf16 v[68:71], v[186:189], v[8:11], v[242:245]
	v_mfma_f32_16x16x32_bf16 v[222:225], v[194:197], v[0:3], v[238:241]
	v_mfma_f32_16x16x32_bf16 v[226:229], v[194:197], v[8:11], v[242:245]
	s_waitcnt vmcnt(2)
	ds_write_b128 v113, v[52:55]
	ds_write_b128 v113, v[48:51] offset:18432
	s_waitcnt lgkmcnt(6)
	v_mfma_f32_16x16x32_bf16 v[64:67], v[190:193], v[4:7], v[64:67]
	v_mfma_f32_16x16x32_bf16 v[68:71], v[190:193], v[12:15], v[68:71]
	v_mfma_f32_16x16x32_bf16 v[222:225], v[198:201], v[4:7], v[222:225]
	v_mfma_f32_16x16x32_bf16 v[226:229], v[198:201], v[12:15], v[226:229]
	s_waitcnt vmcnt(0)
	ds_write_b128 v113, v[56:59] offset:4608
	ds_write_b128 v113, v[60:63] offset:23040
	s_add_i32 s48, s2, 2
	s_min_i32 s48, s48, s47
	s_lshl_b32 s44, s48, 6
	s_lshl_b64 s[48:49], s[44:45], 7
	v_lshl_add_u64 v[52:53], v[158:159], 0, s[48:49]
	v_lshl_add_u64 v[48:49], s[44:45], 1, v[156:157]
	s_or_b32 s44, s44, 32
	s_lshl_b64 s[48:49], s[44:45], 7
	global_load_dwordx4 v[52:55], v[52:53], off
	v_lshl_add_u64 v[56:57], v[158:159], 0, s[48:49]
	v_add_co_u32_e32 v60, vcc, s50, v48
	s_nop 0
	v_addc_co_u32_e32 v61, vcc, 0, v49, vcc
	global_load_dwordx4 v[48:51], v[48:49], off
	global_load_dwordx4 v[56:59], v[56:57], off
	global_load_dwordx4 v[60:63], v[60:61], off
	ds_read_b64 v[186:187], v76 offset:18432
	ds_read_b64 v[188:189], v76 offset:18464
	ds_read_b64 v[190:191], v76 offset:20736
	ds_read_b64 v[192:193], v76 offset:20768
	ds_read_b64 v[194:195], v76 offset:23040
	ds_read_b64 v[196:197], v76 offset:23072
	ds_read_b64 v[198:199], v76 offset:25344
	s_waitcnt lgkmcnt(13)
	ds_read_b64 v[200:201], v76 offset:25376
	s_waitcnt lgkmcnt(13)
	v_mfma_f32_16x16x32_bf16 v[230:233], v[202:205], v[0:3], v[238:241]
	v_mfma_f32_16x16x32_bf16 v[234:237], v[202:205], v[8:11], v[242:245]
	v_mfma_f32_16x16x32_bf16 v[238:241], v[210:213], v[0:3], v[238:241]
	v_mfma_f32_16x16x32_bf16 v[242:245], v[210:213], v[8:11], v[242:245]
	s_waitcnt lgkmcnt(12)
	v_mfma_f32_16x16x32_bf16 v[230:233], v[206:209], v[4:7], v[230:233]
	v_mfma_f32_16x16x32_bf16 v[234:237], v[206:209], v[12:15], v[234:237]
	v_mfma_f32_16x16x32_bf16 v[238:241], v[218:221], v[4:7], v[238:241]
	v_mfma_f32_16x16x32_bf16 v[242:245], v[218:221], v[12:15], v[242:245]
	ds_read_b64 v[202:203], v76 offset:18496
	ds_read_b64 v[204:205], v76 offset:18528
	ds_read_b64 v[206:207], v76 offset:20800
	s_waitcnt lgkmcnt(13)
	ds_read_b64 v[208:209], v76 offset:20832
	ds_read_b64 v[210:211], v76 offset:23104
	s_waitcnt lgkmcnt(13)
	ds_read_b64 v[212:213], v76 offset:23136
	ds_read_b64 v[218:219], v76 offset:25408
	s_waitcnt lgkmcnt(13)
	ds_read_b64 v[220:221], v76 offset:25440
	s_setprio 0
	s_add_u32 s2, s2, 1
	s_addc_u32 s3, s3, 0
	v_exp_f32_e32 v64, v64
	v_exp_f32_e32 v68, v68
	v_exp_f32_e32 v65, v65
	v_exp_f32_e32 v69, v69
	v_exp_f32_e32 v66, v66
	v_exp_f32_e32 v70, v70
	v_exp_f32_e32 v67, v67
	v_exp_f32_e32 v71, v71
	v_pk_add_f32 v[160:161], v[160:161], v[64:65]
	v_pk_add_f32 v[162:163], v[162:163], v[68:69]
	v_pk_add_f32 v[160:161], v[160:161], v[66:67]
	v_pk_add_f32 v[162:163], v[162:163], v[70:71]
	v_exp_f32_e32 v222, v222
	v_exp_f32_e32 v226, v226
	v_exp_f32_e32 v223, v223
	v_exp_f32_e32 v227, v227
	v_exp_f32_e32 v224, v224
	v_exp_f32_e32 v228, v228
	v_exp_f32_e32 v225, v225
	v_exp_f32_e32 v229, v229
	v_pk_add_f32 v[160:161], v[160:161], v[222:223]
	v_pk_add_f32 v[162:163], v[162:163], v[226:227]
	v_pk_add_f32 v[160:161], v[160:161], v[224:225]
	v_pk_add_f32 v[162:163], v[162:163], v[228:229]
	s_waitcnt lgkmcnt(0)
	s_barrier
	v_cvt_pk_bf16_f32 v64, v64, v65
	v_cvt_pk_bf16_f32 v68, v68, v69
	v_cvt_pk_bf16_f32 v65, v66, v67
	v_cvt_pk_bf16_f32 v69, v70, v71
	v_cvt_pk_bf16_f32 v66, v222, v223
	v_cvt_pk_bf16_f32 v70, v226, v227
	v_cvt_pk_bf16_f32 v67, v224, v225
	v_cvt_pk_bf16_f32 v71, v228, v229
	v_exp_f32_e32 v230, v230
	v_exp_f32_e32 v234, v234
	v_mfma_f32_16x16x32_bf16 v[28:31], v[186:189], v[64:67], v[28:31]
	v_exp_f32_e32 v231, v231
	v_exp_f32_e32 v235, v235
	v_exp_f32_e32 v232, v232
	v_exp_f32_e32 v236, v236
	v_mfma_f32_16x16x32_bf16 v[20:23], v[186:189], v[68:71], v[20:23]
	v_exp_f32_e32 v233, v233
	v_exp_f32_e32 v237, v237
	v_pk_add_f32 v[160:161], v[160:161], v[230:231]
	v_pk_add_f32 v[162:163], v[162:163], v[234:235]
	v_mfma_f32_16x16x32_bf16 v[16:19], v[190:193], v[64:67], v[16:19]
	v_pk_add_f32 v[160:161], v[160:161], v[232:233]
	v_pk_add_f32 v[162:163], v[162:163], v[236:237]
	v_exp_f32_e32 v238, v238
	v_exp_f32_e32 v242, v242
	v_mfma_f32_16x16x32_bf16 v[24:27], v[190:193], v[68:71], v[24:27]
	v_exp_f32_e32 v239, v239
	v_exp_f32_e32 v243, v243
	v_exp_f32_e32 v240, v240
	v_exp_f32_e32 v244, v244
	v_mfma_f32_16x16x32_bf16 v[40:43], v[194:197], v[64:67], v[40:43]
	v_exp_f32_e32 v241, v241
	v_exp_f32_e32 v245, v245
	v_pk_add_f32 v[160:161], v[160:161], v[238:239]
	v_pk_add_f32 v[162:163], v[162:163], v[242:243]
	v_mfma_f32_16x16x32_bf16 v[44:47], v[194:197], v[68:71], v[44:47]
	v_pk_add_f32 v[160:161], v[160:161], v[240:241]
	v_pk_add_f32 v[162:163], v[162:163], v[244:245]
	v_cvt_pk_bf16_f32 v230, v230, v231
	v_cvt_pk_bf16_f32 v234, v234, v235
	v_mfma_f32_16x16x32_bf16 v[36:39], v[198:201], v[64:67], v[36:39]
	v_cvt_pk_bf16_f32 v231, v232, v233
	v_cvt_pk_bf16_f32 v235, v236, v237
	v_cvt_pk_bf16_f32 v232, v238, v239
	v_cvt_pk_bf16_f32 v236, v242, v243
	v_mfma_f32_16x16x32_bf16 v[32:35], v[198:201], v[68:71], v[32:35]
	v_cvt_pk_bf16_f32 v233, v240, v241
	v_cvt_pk_bf16_f32 v237, v244, v245
	ds_read_b128 v[186:189], v80 offset:0
	ds_read_b128 v[190:193], v80 offset:64
	ds_read_b128 v[194:197], v80 offset:2304
	ds_read_b128 v[198:201], v80 offset:2368
	s_setprio 2
	v_mfma_f32_16x16x32_bf16 v[28:31], v[202:205], v[230:233], v[28:31]
	v_mfma_f32_16x16x32_bf16 v[20:23], v[202:205], v[234:237], v[20:23]
	v_mfma_f32_16x16x32_bf16 v[16:19], v[206:209], v[230:233], v[16:19]
	v_mfma_f32_16x16x32_bf16 v[24:27], v[206:209], v[234:237], v[24:27]
	v_mfma_f32_16x16x32_bf16 v[40:43], v[210:213], v[230:233], v[40:43]
	v_mfma_f32_16x16x32_bf16 v[44:47], v[210:213], v[234:237], v[44:47]
	v_mfma_f32_16x16x32_bf16 v[36:39], v[218:221], v[230:233], v[36:39]
	v_mfma_f32_16x16x32_bf16 v[32:35], v[218:221], v[234:237], v[32:35]
	s_cmp_lg_u32 s46, s2
	s_cbranch_scc1 .LBB0_868
	s_branch .Lsel5_done
.Lsel5_disp:
	s_cmp_eq_u32 s48, 1
	s_cbranch_scc1 .Lsel5_b0
	s_cmp_eq_u32 s48, 2
	s_cbranch_scc1 .Lsel5_b1
	s_waitcnt vmcnt(2)
	ds_write_b128 v113, v[52:55]
	ds_write_b128 v113, v[48:51] offset:18432
	s_waitcnt vmcnt(0)
	ds_write_b128 v113, v[56:59] offset:4608
	ds_write_b128 v113, v[60:63] offset:23040
	s_add_i32 s48, s2, 2
	s_min_i32 s48, s48, s47
	s_lshl_b32 s44, s48, 6
	s_lshl_b64 s[48:49], s[44:45], 7
	v_lshl_add_u64 v[52:53], v[158:159], 0, s[48:49]
	v_lshl_add_u64 v[48:49], s[44:45], 1, v[156:157]
	s_or_b32 s44, s44, 32
	s_lshl_b64 s[48:49], s[44:45], 7
	global_load_dwordx4 v[52:55], v[52:53], off
	v_lshl_add_u64 v[56:57], v[158:159], 0, s[48:49]
	v_add_co_u32_e32 v60, vcc, s50, v48
	s_nop 0
	v_addc_co_u32_e32 v61, vcc, 0, v49, vcc
	global_load_dwordx4 v[48:51], v[48:49], off
	global_load_dwordx4 v[56:59], v[56:57], off
	global_load_dwordx4 v[60:63], v[60:61], off
	s_setprio 0
	s_add_u32 s2, s2, 1
	s_addc_u32 s3, s3, 0
	s_waitcnt lgkmcnt(0)
	s_barrier
	ds_read_b128 v[186:189], v80 offset:0
	ds_read_b128 v[190:193], v80 offset:64
	ds_read_b128 v[194:197], v80 offset:2304
	ds_read_b128 v[198:201], v80 offset:2368
	s_setprio 2
	s_cmp_lg_u32 s46, s2
	s_cbranch_scc1 .LBB0_868
	s_branch .Lsel5_done
.Lsel5_b0:
	v_not_b32_e32 v246, v246
	v_bfe_i32 v246, v246, 0, 1
	v_and_b32_e32 v238, 0xf149f2ca, v246
	v_and_b32_e32 v239, 0xf149f2ca, v246
	v_and_b32_e32 v240, 0xf149f2ca, v246
	v_and_b32_e32 v241, 0xf149f2ca, v246
	s_waitcnt lgkmcnt(5)
	v_mfma_f32_16x16x32_bf16 v[64:67], v[186:189], v[0:3], v[238:241]
	v_mfma_f32_16x16x32_bf16 v[222:225], v[194:197], v[0:3], v[238:241]
	s_waitcnt vmcnt(2)
	ds_write_b128 v113, v[52:55]
	ds_write_b128 v113, v[48:51] offset:18432
	s_waitcnt lgkmcnt(6)
	v_mfma_f32_16x16x32_bf16 v[64:67], v[190:193], v[4:7], v[64:67]
	v_mfma_f32_16x16x32_bf16 v[222:225], v[198:201], v[4:7], v[222:225]
	s_waitcnt vmcnt(0)
	ds_write_b128 v113, v[56:59] offset:4608
	ds_write_b128 v113, v[60:63] offset:23040
	s_add_i32 s48, s2, 2
	s_min_i32 s48, s48, s47
	s_lshl_b32 s44, s48, 6
	s_lshl_b64 s[48:49], s[44:45], 7
	v_lshl_add_u64 v[52:53], v[158:159], 0, s[48:49]
	v_lshl_add_u64 v[48:49], s[44:45], 1, v[156:157]
	s_or_b32 s44, s44, 32
	s_lshl_b64 s[48:49], s[44:45], 7
	global_load_dwordx4 v[52:55], v[52:53], off
	v_lshl_add_u64 v[56:57], v[158:159], 0, s[48:49]
	v_add_co_u32_e32 v60, vcc, s50, v48
	s_nop 0
	v_addc_co_u32_e32 v61, vcc, 0, v49, vcc
	global_load_dwordx4 v[48:51], v[48:49], off
	global_load_dwordx4 v[56:59], v[56:57], off
	global_load_dwordx4 v[60:63], v[60:61], off
	ds_read_b64 v[186:187], v76 offset:18432
	ds_read_b64 v[188:189], v76 offset:18464
	ds_read_b64 v[190:191], v76 offset:20736
	ds_read_b64 v[192:193], v76 offset:20768
	ds_read_b64 v[194:195], v76 offset:23040
	ds_read_b64 v[196:197], v76 offset:23072
	ds_read_b64 v[198:199], v76 offset:25344
	s_waitcnt lgkmcnt(13)
	ds_read_b64 v[200:201], v76 offset:25376
	s_waitcnt lgkmcnt(13)
	v_mfma_f32_16x16x32_bf16 v[230:233], v[202:205], v[0:3], v[238:241]
	v_mfma_f32_16x16x32_bf16 v[238:241], v[210:213], v[0:3], v[238:241]
	s_waitcnt lgkmcnt(12)
	v_mfma_f32_16x16x32_bf16 v[230:233], v[206:209], v[4:7], v[230:233]
	v_mfma_f32_16x16x32_bf16 v[238:241], v[218:221], v[4:7], v[238:241]
	ds_read_b64 v[202:203], v76 offset:18496
	ds_read_b64 v[204:205], v76 offset:18528
	ds_read_b64 v[206:207], v76 offset:20800
	s_waitcnt lgkmcnt(13)
	ds_read_b64 v[208:209], v76 offset:20832
	ds_read_b64 v[210:211], v76 offset:23104
	s_waitcnt lgkmcnt(13)
	ds_read_b64 v[212:213], v76 offset:23136
	ds_read_b64 v[218:219], v76 offset:25408
	s_waitcnt lgkmcnt(13)
	ds_read_b64 v[220:221], v76 offset:25440
	s_setprio 0
	s_add_u32 s2, s2, 1
	s_addc_u32 s3, s3, 0
	v_exp_f32_e32 v64, v64
	v_exp_f32_e32 v65, v65
	v_exp_f32_e32 v66, v66
	v_exp_f32_e32 v67, v67
	v_pk_add_f32 v[160:161], v[160:161], v[64:65]
	v_pk_add_f32 v[160:161], v[160:161], v[66:67]
	v_exp_f32_e32 v222, v222
	v_exp_f32_e32 v223, v223
	v_exp_f32_e32 v224, v224
	v_exp_f32_e32 v225, v225
	v_pk_add_f32 v[160:161], v[160:161], v[222:223]
	v_pk_add_f32 v[160:161], v[160:161], v[224:225]
	s_waitcnt lgkmcnt(0)
	s_barrier
	v_cvt_pk_bf16_f32 v64, v64, v65
	v_cvt_pk_bf16_f32 v65, v66, v67
	v_cvt_pk_bf16_f32 v66, v222, v223
	v_cvt_pk_bf16_f32 v67, v224, v225
	v_exp_f32_e32 v230, v230
	v_exp_f32_e32 v231, v231
	v_mfma_f32_16x16x32_bf16 v[28:31], v[186:189], v[64:67], v[28:31]
	v_exp_f32_e32 v232, v232
	v_exp_f32_e32 v233, v233
	v_pk_add_f32 v[160:161], v[160:161], v[230:231]
	v_pk_add_f32 v[160:161], v[160:161], v[232:233]
	v_mfma_f32_16x16x32_bf16 v[16:19], v[190:193], v[64:67], v[16:19]
	v_exp_f32_e32 v238, v238
	v_exp_f32_e32 v239, v239
	v_exp_f32_e32 v240, v240
	v_exp_f32_e32 v241, v241
	v_mfma_f32_16x16x32_bf16 v[40:43], v[194:197], v[64:67], v[40:43]
	v_pk_add_f32 v[160:161], v[160:161], v[238:239]
	v_pk_add_f32 v[160:161], v[160:161], v[240:241]
	v_cvt_pk_bf16_f32 v230, v230, v231
	v_cvt_pk_bf16_f32 v231, v232, v233
	v_mfma_f32_16x16x32_bf16 v[36:39], v[198:201], v[64:67], v[36:39]
	v_cvt_pk_bf16_f32 v232, v238, v239
	v_cvt_pk_bf16_f32 v233, v240, v241
	ds_read_b128 v[186:189], v80 offset:0
	ds_read_b128 v[190:193], v80 offset:64
	ds_read_b128 v[194:197], v80 offset:2304
	ds_read_b128 v[198:201], v80 offset:2368
	s_setprio 2
	v_mfma_f32_16x16x32_bf16 v[28:31], v[202:205], v[230:233], v[28:31]
	v_mfma_f32_16x16x32_bf16 v[16:19], v[206:209], v[230:233], v[16:19]
	v_mfma_f32_16x16x32_bf16 v[40:43], v[210:213], v[230:233], v[40:43]
	v_mfma_f32_16x16x32_bf16 v[36:39], v[218:221], v[230:233], v[36:39]
	s_cmp_lg_u32 s46, s2
	s_cbranch_scc1 .LBB0_868
	s_branch .Lsel5_done
.Lsel5_b1:
	v_not_b32_e32 v247, v244
	v_bfe_i32 v247, v247, 0, 1
	v_and_b32_e32 v242, 0xf149f2ca, v247
	v_and_b32_e32 v243, 0xf149f2ca, v247
	v_and_b32_e32 v244, 0xf149f2ca, v247
	v_and_b32_e32 v245, 0xf149f2ca, v247
	s_waitcnt lgkmcnt(5)
	v_mfma_f32_16x16x32_bf16 v[68:71], v[186:189], v[8:11], v[242:245]
	v_mfma_f32_16x16x32_bf16 v[226:229], v[194:197], v[8:11], v[242:245]
	s_waitcnt vmcnt(2)
	ds_write_b128 v113, v[52:55]
	ds_write_b128 v113, v[48:51] offset:18432
	s_waitcnt lgkmcnt(6)
	v_mfma_f32_16x16x32_bf16 v[68:71], v[190:193], v[12:15], v[68:71]
	v_mfma_f32_16x16x32_bf16 v[226:229], v[198:201], v[12:15], v[226:229]
	s_waitcnt vmcnt(0)
	ds_write_b128 v113, v[56:59] offset:4608
	ds_write_b128 v113, v[60:63] offset:23040
	s_add_i32 s48, s2, 2
	s_min_i32 s48, s48, s47
	s_lshl_b32 s44, s48, 6
	s_lshl_b64 s[48:49], s[44:45], 7
	v_lshl_add_u64 v[52:53], v[158:159], 0, s[48:49]
	v_lshl_add_u64 v[48:49], s[44:45], 1, v[156:157]
	s_or_b32 s44, s44, 32
	s_lshl_b64 s[48:49], s[44:45], 7
	global_load_dwordx4 v[52:55], v[52:53], off
	v_lshl_add_u64 v[56:57], v[158:159], 0, s[48:49]
	v_add_co_u32_e32 v60, vcc, s50, v48
	s_nop 0
	v_addc_co_u32_e32 v61, vcc, 0, v49, vcc
	global_load_dwordx4 v[48:51], v[48:49], off
	global_load_dwordx4 v[56:59], v[56:57], off
	global_load_dwordx4 v[60:63], v[60:61], off
	ds_read_b64 v[186:187], v76 offset:18432
	ds_read_b64 v[188:189], v76 offset:18464
	ds_read_b64 v[190:191], v76 offset:20736
	ds_read_b64 v[192:193], v76 offset:20768
	ds_read_b64 v[194:195], v76 offset:23040
	ds_read_b64 v[196:197], v76 offset:23072
	ds_read_b64 v[198:199], v76 offset:25344
	s_waitcnt lgkmcnt(13)
	ds_read_b64 v[200:201], v76 offset:25376
	s_waitcnt lgkmcnt(13)
	v_mfma_f32_16x16x32_bf16 v[234:237], v[202:205], v[8:11], v[242:245]
	v_mfma_f32_16x16x32_bf16 v[242:245], v[210:213], v[8:11], v[242:245]
	s_waitcnt lgkmcnt(12)
	v_mfma_f32_16x16x32_bf16 v[234:237], v[206:209], v[12:15], v[234:237]
	v_mfma_f32_16x16x32_bf16 v[242:245], v[218:221], v[12:15], v[242:245]
	ds_read_b64 v[202:203], v76 offset:18496
	ds_read_b64 v[204:205], v76 offset:18528
	ds_read_b64 v[206:207], v76 offset:20800
	s_waitcnt lgkmcnt(13)
	ds_read_b64 v[208:209], v76 offset:20832
	ds_read_b64 v[210:211], v76 offset:23104
	s_waitcnt lgkmcnt(13)
	ds_read_b64 v[212:213], v76 offset:23136
	ds_read_b64 v[218:219], v76 offset:25408
	s_waitcnt lgkmcnt(13)
	ds_read_b64 v[220:221], v76 offset:25440
	s_setprio 0
	s_add_u32 s2, s2, 1
	s_addc_u32 s3, s3, 0
	v_exp_f32_e32 v68, v68
	v_exp_f32_e32 v69, v69
	v_exp_f32_e32 v70, v70
	v_exp_f32_e32 v71, v71
	v_pk_add_f32 v[162:163], v[162:163], v[68:69]
	v_pk_add_f32 v[162:163], v[162:163], v[70:71]
	v_exp_f32_e32 v226, v226
	v_exp_f32_e32 v227, v227
	v_exp_f32_e32 v228, v228
	v_exp_f32_e32 v229, v229
	v_pk_add_f32 v[162:163], v[162:163], v[226:227]
	v_pk_add_f32 v[162:163], v[162:163], v[228:229]
	s_waitcnt lgkmcnt(0)
	s_barrier
	v_cvt_pk_bf16_f32 v68, v68, v69
	v_cvt_pk_bf16_f32 v69, v70, v71
	v_cvt_pk_bf16_f32 v70, v226, v227
	v_cvt_pk_bf16_f32 v71, v228, v229
	v_exp_f32_e32 v234, v234
	v_exp_f32_e32 v235, v235
	v_mfma_f32_16x16x32_bf16 v[20:23], v[186:189], v[68:71], v[20:23]
	v_exp_f32_e32 v236, v236
	v_exp_f32_e32 v237, v237
	v_pk_add_f32 v[162:163], v[162:163], v[234:235]
	v_pk_add_f32 v[162:163], v[162:163], v[236:237]
	v_mfma_f32_16x16x32_bf16 v[24:27], v[190:193], v[68:71], v[24:27]
	v_exp_f32_e32 v242, v242
	v_exp_f32_e32 v243, v243
	v_exp_f32_e32 v244, v244
	v_exp_f32_e32 v245, v245
	v_mfma_f32_16x16x32_bf16 v[44:47], v[194:197], v[68:71], v[44:47]
	v_pk_add_f32 v[162:163], v[162:163], v[242:243]
	v_pk_add_f32 v[162:163], v[162:163], v[244:245]
	v_cvt_pk_bf16_f32 v234, v234, v235
	v_cvt_pk_bf16_f32 v235, v236, v237
	v_mfma_f32_16x16x32_bf16 v[32:35], v[198:201], v[68:71], v[32:35]
	v_cvt_pk_bf16_f32 v236, v242, v243
	v_cvt_pk_bf16_f32 v237, v244, v245
	ds_read_b128 v[186:189], v80 offset:0
	ds_read_b128 v[190:193], v80 offset:64
	ds_read_b128 v[194:197], v80 offset:2304
	ds_read_b128 v[198:201], v80 offset:2368
	s_setprio 2
	v_mfma_f32_16x16x32_bf16 v[20:23], v[202:205], v[234:237], v[20:23]
	v_mfma_f32_16x16x32_bf16 v[24:27], v[206:209], v[234:237], v[24:27]
	v_mfma_f32_16x16x32_bf16 v[44:47], v[210:213], v[234:237], v[44:47]
	v_mfma_f32_16x16x32_bf16 v[32:35], v[218:221], v[234:237], v[32:35]
	s_cmp_lg_u32 s46, s2
	s_cbranch_scc1 .LBB0_868
.Lsel5_done:
	s_waitcnt lgkmcnt(0)
	s_setprio 1
	v_add_f32_e32 v160, v160, v161
	v_add_f32_e32 v161, v162, v163
	s_waitcnt vmcnt(3)
	v_mov_b32_e32 v53, v160
	v_mov_b32_e32 v52, v161
